# K-loop: LDS fragment reads no longer waited before the barrier (lgkmcnt wait only after it, at the first MFMA)
# baseline (speedup 1.0000x reference)
; #define PG8_STAGE(bufoff, gbase, voff) do { _Pragma("unroll") for (int _i = 0; _i < 2; ++_i) \
;     __builtin_amdgcn_global_load_lds((const unsigned*)((const char*)(gbase) + (voff)[_i]), (LAS unsigned*)(lds + (bufoff) + ldsw + _i * 8192), 16, 0, 0); } while (0)
; #define PG8_LDA(dst, b, h) do { _Pragma("unroll") for (int m = 0; m < 4; ++m) _Pragma("unroll") for (int k = 0; k < 2; ++k) dst[m][k] = *(const LAS bf16x8*)(lds + PG8_SA(b, h) + aoff + m * 2048 + k * 1024); } while (0)
; #define PG8_LDB(dst, b, h) do { _Pragma("unroll") for (int n = 0; n < 2; ++n) _Pragma("unroll") for (int k = 0; k < 2; ++k) dst[n][k] = *(const LAS bf16x8*)(lds + PG8_SB(b, h) + boff + n * 2048 + k * 1024); } while (0)
; #define PG8_MMA(ai, bj, At, Bt) do { __builtin_amdgcn_s_setprio(1); _Pragma("unroll") for (int m = 0; m < 4; ++m) _Pragma("unroll") for (int n = 0; n < 2; ++n) _Pragma("unroll") for (int k = 0; k < 2; ++k) \
;     acc[ai][bj][m][n] = __builtin_amdgcn_mfma_f32_16x16x32_bf16(Bt[n][k], At[m][k], acc[ai][bj][m][n], 0, 0, 0); __builtin_amdgcn_s_setprio(0); } while (0)
; #define PG8_WAIT_V(n) asm volatile("s_waitcnt vmcnt(" #n ")" ::: "memory")
; #define PG8_WAIT_L(n) asm volatile("s_waitcnt lgkmcnt(" #n ")" ::: "memory")
; #define PG8_BAR __builtin_amdgcn_s_barrier()
; __device__ __forceinline__ void gemm_phase(const Ctx& cx, LAS unsigned char* lds, const GemmDesc& g) {
;     ...
;     for (int t = 0; t < nt; t += 2) {
;       const bool last = (t == nt - 2);
;       const char* a1 = ktile_ptr(cA1, cA2, t + 1, ksplit, kstepA);
;       const char* a2 = last ? ktile_ptr(nA1, nA2, 0, ksplit, kstepA) : ktile_ptr(cA1, cA2, t + 2, ksplit, kstepA);
;       const char* a3 = last ? ktile_ptr(nA1, nA2, 1, ksplit, kstepA) : ktile_ptr(cA1, cA2, t + 3, ksplit, kstepA);
;       const char* b2 = last ? nB : cB + (size_t)(t + 2) * kstepB; const char* b3 = b2 + kstepB;
;       PG8_LDB(B0, 0, 0); PG8_LDB(B1, 0, 1); PG8_SCHED; PG8_LDA(At, 0, 0); PG8_STAGE(PG8_SA(1, 1), a1 + hstepA, voffA);
;       PG8_WAIT_V(8); PG8_WAIT_L(0); PG8_BAR; PG8_MMA(0, 0, At, B0); PG8_MMA(0, 1, At, B1); PG8_BAR; PG8_SCHED;
;       PG8_LDA(At, 0, 1); PG8_STAGE(PG8_SB(0, 0), b2, voffB); PG8_STAGE(PG8_SB(0, 1), b2 + hstepB, voffB); PG8_STAGE(PG8_SA(0, 0), a2, voffA);
;       PG8_WAIT_V(8); PG8_WAIT_L(0); PG8_BAR; PG8_MMA(1, 0, At, B0); PG8_MMA(1, 1, At, B1); PG8_BAR; PG8_SCHED;
.LBB0_357:
	s_add_u32 s12, s60, s18
	s_addc_u32 s13, s61, s19
	s_add_u32 s16, s24, s16
	s_addc_u32 s17, s25, s17
	s_add_u32 s20, s12, s68
	s_addc_u32 s21, s13, s69
	s_add_u32 s52, s14, 0x100
	s_addc_u32 s53, s15, 0
	s_mov_b32 s6, 0
	s_add_i32 s7, s6, 1
	s_sub_i32 s14, s7, s41
	s_min_u32 s76, s7, s14
	s_cmp_lt_u32 s7, s41
	s_cselect_b32 s7, s9, s17
	s_cselect_b32 s54, s8, s16
	s_lshl_b64 s[14:15], s[76:77], s80
	s_add_u32 s55, s54, s14
	s_addc_u32 s73, s7, s15
	s_add_i32 s76, 0, 0x10000
	v_add_u32_e32 v96, s76, v252
	s_add_i32 vcc_lo, 0, 0x14000
	ds_read_b128 v[130:133], v96
	ds_read_b128 v[134:137], v96 offset:1024
	ds_read_b128 v[138:141], v96 offset:2048
	ds_read_b128 v[142:145], v96 offset:3072
	v_add_u32_e32 v96, vcc_lo, v252
	ds_read_b128 v[146:149], v96
	ds_read_b128 v[150:153], v96 offset:1024
	ds_read_b128 v[154:157], v96 offset:2048
	ds_read_b128 v[158:161], v96 offset:3072
	s_add_u32 s72, s55, s28
	s_addc_u32 s73, s73, s29
	v_lshl_add_u64 v[194:195], s[72:73], 0, v[210:211]
	s_add_i32 m0, s51, 0xc000
	ds_read_b128 v[162:165], v237
	ds_read_b128 v[166:169], v237 offset:1024
	ds_read_b128 v[170:173], v237 offset:2048
	ds_read_b128 v[174:177], v237 offset:3072
	ds_read_b128 v[178:181], v237 offset:4096
	ds_read_b128 v[182:185], v237 offset:5120
	ds_read_b128 v[186:189], v237 offset:6144
	ds_read_b128 v[190:193], v237 offset:7168
	global_load_lds_dwordx4 v[194:195], off
	v_lshl_add_u64 v[194:195], s[72:73], 0, v[212:213]
	s_add_i32 m0, s51, 0xe000
	s_nop 0
	global_load_lds_dwordx4 v[194:195], off
	s_waitcnt vmcnt(8)
	s_barrier
	s_waitcnt lgkmcnt(0)
	v_mfma_f32_16x16x32_bf16 v[126:129], v[130:133], v[162:165], 0
	v_mfma_f32_16x16x32_bf16 v[126:129], v[134:137], v[166:169], v[126:129]
	s_add_i32 s54, s6, 2
	s_cmp_lt_u32 s54, s41
	v_mfma_f32_16x16x32_bf16 v[122:125], v[142:145], v[166:169], 0
	s_cselect_b64 s[14:15], -1, 0
	s_and_b64 s[58:59], s[14:15], exec
	v_mfma_f32_16x16x32_bf16 v[122:125], v[138:141], v[162:165], v[122:125]
	s_cselect_b32 s7, 0, s41
	s_sub_i32 s7, s6, s7
	v_mfma_f32_16x16x32_bf16 v[118:121], v[146:149], v[162:165], 0
	s_add_i32 s76, s7, 2
	s_and_b64 s[14:15], s[14:15], exec
	v_mfma_f32_16x16x32_bf16 v[118:121], v[150:153], v[166:169], v[118:121]
	s_cselect_b32 s7, s9, s17
	s_cselect_b32 s58, s8, s16
	v_mfma_f32_16x16x32_bf16 v[114:117], v[158:161], v[166:169], 0
	s_lshl_b64 s[14:15], s[76:77], s80
	s_add_u32 s72, s58, s14
	v_mfma_f32_16x16x32_bf16 v[114:117], v[154:157], v[162:165], v[114:117]
	s_addc_u32 s7, s7, s15
	s_add_i32 s14, s6, 3
	v_mfma_f32_16x16x32_bf16 v[98:101], v[154:157], v[170:173], 0
	s_cmp_lt_u32 s14, s41
	s_cselect_b64 s[14:15], -1, 0
	v_mfma_f32_16x16x32_bf16 v[98:101], v[158:161], v[174:177], v[98:101]
	s_and_b64 s[58:59], s[14:15], exec
	s_cselect_b32 s58, 0, s41
	v_mfma_f32_16x16x32_bf16 v[102:105], v[150:153], v[174:177], 0
	s_sub_i32 s58, s6, s58
	s_add_i32 s76, s58, 3
	v_mfma_f32_16x16x32_bf16 v[102:105], v[146:149], v[170:173], v[102:105]
	s_and_b64 s[14:15], s[14:15], exec
	s_cselect_b32 s58, s9, s17
	v_mfma_f32_16x16x32_bf16 v[106:109], v[138:141], v[170:173], 0
	s_cselect_b32 s59, s8, s16
	s_lshl_b64 s[14:15], s[76:77], s80
	v_mfma_f32_16x16x32_bf16 v[106:109], v[142:145], v[174:177], v[106:109]
	s_add_u32 s59, s59, s14
	s_addc_u32 s58, s58, s15
	v_mfma_f32_16x16x32_bf16 v[110:113], v[134:137], v[174:177], 0
	s_cmp_eq_u32 s39, s6
	s_cselect_b32 s15, s13, s7
	v_mfma_f32_16x16x32_bf16 v[110:113], v[130:133], v[170:173], v[110:113]
	s_cselect_b32 s14, s12, s72
	s_cselect_b32 s7, s21, s58
	v_mfma_f32_16x16x32_bf16 v[92:95], v[130:133], v[178:181], 0
	s_cselect_b32 s6, s20, s59
	s_cselect_b32 s59, s97, s53
	v_mfma_f32_16x16x32_bf16 v[92:95], v[134:137], v[182:185], v[92:95]
	s_cselect_b32 s58, s96, s52
	s_mov_b32 s76, 0x10000
	v_mfma_f32_16x16x32_bf16 v[88:91], v[142:145], v[182:185], 0
	v_mfma_f32_16x16x32_bf16 v[88:91], v[138:141], v[178:181], v[88:91]
	v_mfma_f32_16x16x32_bf16 v[84:87], v[146:149], v[178:181], 0
	v_mfma_f32_16x16x32_bf16 v[84:87], v[150:153], v[182:185], v[84:87]
	v_mfma_f32_16x16x32_bf16 v[80:83], v[158:161], v[182:185], 0
	v_mfma_f32_16x16x32_bf16 v[80:83], v[154:157], v[178:181], v[80:83]
	v_mfma_f32_16x16x32_bf16 v[64:67], v[154:157], v[186:189], 0
	v_mfma_f32_16x16x32_bf16 v[64:67], v[158:161], v[190:193], v[64:67]
	v_mfma_f32_16x16x32_bf16 v[68:71], v[150:153], v[190:193], 0
	v_mfma_f32_16x16x32_bf16 v[68:71], v[146:149], v[186:189], v[68:71]
	v_mfma_f32_16x16x32_bf16 v[72:75], v[138:141], v[186:189], 0
	v_mfma_f32_16x16x32_bf16 v[72:75], v[142:145], v[190:193], v[72:75]
	v_mfma_f32_16x16x32_bf16 v[76:79], v[134:137], v[190:193], 0
	v_mfma_f32_16x16x32_bf16 v[76:79], v[130:133], v[186:189], v[76:79]
	s_barrier
	s_add_i32 s55, s76, s36
	v_lshl_add_u64 v[194:195], s[58:59], 0, v[216:217]
	s_mov_b32 m0, s55
	ds_read_b128 v[162:165], v237 offset:16384
	ds_read_b128 v[166:169], v237 offset:17408
	ds_read_b128 v[170:173], v237 offset:18432
	ds_read_b128 v[174:177], v237 offset:19456
	ds_read_b128 v[178:181], v237 offset:20480
	ds_read_b128 v[182:185], v237 offset:21504
	ds_read_b128 v[186:189], v237 offset:22528
	ds_read_b128 v[190:193], v237 offset:23552
	global_load_lds_dwordx4 v[194:195], off
	s_add_i32 m0, s55, 0x2000
	v_lshl_add_u64 v[196:197], s[58:59], 0, v[214:215]
	s_add_u32 s58, s58, s30
	s_addc_u32 s59, s59, s31
	s_add_i32 s55, vcc_lo, s36
	global_load_lds_dwordx4 v[196:197], off
	v_lshl_add_u64 v[198:199], s[58:59], 0, v[216:217]
	s_mov_b32 m0, s55
	v_lshl_add_u64 v[200:201], s[58:59], 0, v[214:215]
	global_load_lds_dwordx4 v[198:199], off
	s_add_i32 m0, s55, 0x2000
	v_lshl_add_u64 v[202:203], s[14:15], 0, v[210:211]
	global_load_lds_dwordx4 v[200:201], off
	s_mov_b32 m0, s51
	s_nop 0
	global_load_lds_dwordx4 v[202:203], off
	v_lshl_add_u64 v[202:203], s[14:15], 0, v[212:213]
	s_mov_b32 m0, s43
	s_nop 0
	global_load_lds_dwordx4 v[202:203], off
	s_waitcnt vmcnt(8)
	s_barrier
; #define PG8_STAGE(bufoff, gbase, voff) do { _Pragma("unroll") for (int _i = 0; _i < 2; ++_i) \
;     __builtin_amdgcn_global_load_lds((const unsigned*)((const char*)(gbase) + (voff)[_i]), (LAS unsigned*)(lds + (bufoff) + ldsw + _i * 8192), 16, 0, 0); } while (0)
; #define PG8_LDA(dst, b, h) do { _Pragma("unroll") for (int m = 0; m < 4; ++m) _Pragma("unroll") for (int k = 0; k < 2; ++k) dst[m][k] = *(const LAS bf16x8*)(lds + PG8_SA(b, h) + aoff + m * 2048 + k * 1024); } while (0)
; #define PG8_LDB(dst, b, h) do { _Pragma("unroll") for (int n = 0; n < 2; ++n) _Pragma("unroll") for (int k = 0; k < 2; ++k) dst[n][k] = *(const LAS bf16x8*)(lds + PG8_SB(b, h) + boff + n * 2048 + k * 1024); } while (0)
; #define PG8_MMA(ai, bj, At, Bt) do { __builtin_amdgcn_s_setprio(1); _Pragma("unroll") for (int m = 0; m < 4; ++m) _Pragma("unroll") for (int n = 0; n < 2; ++n) _Pragma("unroll") for (int k = 0; k < 2; ++k) \
;     acc[ai][bj][m][n] = __builtin_amdgcn_mfma_f32_16x16x32_bf16(Bt[n][k], At[m][k], acc[ai][bj][m][n], 0, 0, 0); __builtin_amdgcn_s_setprio(0); } while (0)
; #define PG8_WAIT_V(n) asm volatile("s_waitcnt vmcnt(" #n ")" ::: "memory")
; #define PG8_WAIT_L(n) asm volatile("s_waitcnt lgkmcnt(" #n ")" ::: "memory")
; #define PG8_BAR __builtin_amdgcn_s_barrier()
; #define PG8_SCHED __builtin_amdgcn_sched_barrier(0)
; __device__ __forceinline__ void gemm_phase(const Ctx& cx, LAS unsigned char* lds, const GemmDesc& g) {
;     ...
;       PG8_LDB(B0, 0, 0); PG8_LDB(B1, 0, 1); PG8_SCHED; PG8_LDA(At, 0, 0); PG8_STAGE(PG8_SA(1, 1), a1 + hstepA, voffA);
;       PG8_WAIT_V(8); PG8_WAIT_L(0); PG8_BAR; PG8_MMA(0, 0, At, B0); PG8_MMA(0, 1, At, B1); PG8_BAR; PG8_SCHED;
;       PG8_LDA(At, 0, 1); PG8_STAGE(PG8_SB(0, 0), b2, voffB); PG8_STAGE(PG8_SB(0, 1), b2 + hstepB, voffB); PG8_STAGE(PG8_SA(0, 0), a2, voffA);
;       PG8_WAIT_V(8); PG8_WAIT_L(0); PG8_BAR; PG8_MMA(1, 0, At, B0); PG8_MMA(1, 1, At, B1); PG8_BAR; PG8_SCHED;
	s_waitcnt lgkmcnt(0)
	v_mfma_f32_16x16x32_bf16 v[60:63], v[130:133], v[162:165], 0
	v_mfma_f32_16x16x32_bf16 v[60:63], v[134:137], v[166:169], v[60:63]
	v_mfma_f32_16x16x32_bf16 v[56:59], v[142:145], v[166:169], 0
	v_mfma_f32_16x16x32_bf16 v[56:59], v[138:141], v[162:165], v[56:59]
	v_mfma_f32_16x16x32_bf16 v[52:55], v[146:149], v[162:165], 0
	v_mfma_f32_16x16x32_bf16 v[52:55], v[150:153], v[166:169], v[52:55]
	v_mfma_f32_16x16x32_bf16 v[48:51], v[158:161], v[166:169], 0
	v_mfma_f32_16x16x32_bf16 v[48:51], v[154:157], v[162:165], v[48:51]
	v_mfma_f32_16x16x32_bf16 v[32:35], v[154:157], v[170:173], 0
	v_mfma_f32_16x16x32_bf16 v[32:35], v[158:161], v[174:177], v[32:35]
	v_mfma_f32_16x16x32_bf16 v[36:39], v[150:153], v[174:177], 0
	v_mfma_f32_16x16x32_bf16 v[36:39], v[146:149], v[170:173], v[36:39]
	v_mfma_f32_16x16x32_bf16 v[40:43], v[138:141], v[170:173], 0
	v_mfma_f32_16x16x32_bf16 v[40:43], v[142:145], v[174:177], v[40:43]
	v_mfma_f32_16x16x32_bf16 v[44:47], v[134:137], v[174:177], 0
	v_mfma_f32_16x16x32_bf16 v[44:47], v[130:133], v[170:173], v[44:47]
	v_mfma_f32_16x16x32_bf16 v[28:31], v[130:133], v[178:181], 0
	v_mfma_f32_16x16x32_bf16 v[28:31], v[134:137], v[182:185], v[28:31]
	v_mfma_f32_16x16x32_bf16 v[24:27], v[142:145], v[182:185], 0
	v_mfma_f32_16x16x32_bf16 v[24:27], v[138:141], v[178:181], v[24:27]
	v_mfma_f32_16x16x32_bf16 v[20:23], v[146:149], v[178:181], 0
	v_mfma_f32_16x16x32_bf16 v[20:23], v[150:153], v[182:185], v[20:23]
	v_mfma_f32_16x16x32_bf16 v[16:19], v[158:161], v[182:185], 0
	v_mfma_f32_16x16x32_bf16 v[16:19], v[154:157], v[178:181], v[16:19]
	v_mfma_f32_16x16x32_bf16 v[0:3], v[154:157], v[186:189], 0
	v_mfma_f32_16x16x32_bf16 v[0:3], v[158:161], v[190:193], v[0:3]
	v_mfma_f32_16x16x32_bf16 v[4:7], v[150:153], v[190:193], 0
	v_mfma_f32_16x16x32_bf16 v[4:7], v[146:149], v[186:189], v[4:7]
	v_mfma_f32_16x16x32_bf16 v[8:11], v[138:141], v[186:189], 0
	v_mfma_f32_16x16x32_bf16 v[8:11], v[142:145], v[190:193], v[8:11]
	v_mfma_f32_16x16x32_bf16 v[12:15], v[134:137], v[190:193], 0
	v_mfma_f32_16x16x32_bf16 v[12:15], v[130:133], v[186:189], v[12:15]
	s_barrier
	s_branch .Lk_p2
.LBB0_358:
	s_add_i32 s7, s6, 1
	s_sub_i32 s14, s7, s41
	s_min_u32 s76, s7, s14
	s_cmp_lt_u32 s7, s41
	s_cselect_b32 s7, s9, s17
	s_cselect_b32 s54, s8, s16
	s_lshl_b64 s[14:15], s[76:77], s80
	s_add_u32 s55, s54, s14
	s_addc_u32 s73, s7, s15
	s_add_i32 s76, 0, 0x10000
	v_add_u32_e32 v96, s76, v252
	s_add_i32 vcc_lo, 0, 0x14000
	ds_read_b128 v[130:133], v96
	ds_read_b128 v[134:137], v96 offset:1024
	ds_read_b128 v[138:141], v96 offset:2048
	ds_read_b128 v[142:145], v96 offset:3072
	v_add_u32_e32 v96, vcc_lo, v252
	ds_read_b128 v[146:149], v96
	ds_read_b128 v[150:153], v96 offset:1024
	ds_read_b128 v[154:157], v96 offset:2048
	ds_read_b128 v[158:161], v96 offset:3072
	s_add_u32 s72, s55, s28
	s_addc_u32 s73, s73, s29
	v_lshl_add_u64 v[194:195], s[72:73], 0, v[210:211]
	s_add_i32 m0, s51, 0xc000
	ds_read_b128 v[162:165], v237
	ds_read_b128 v[166:169], v237 offset:1024
	ds_read_b128 v[170:173], v237 offset:2048
	ds_read_b128 v[174:177], v237 offset:3072
	ds_read_b128 v[178:181], v237 offset:4096
	ds_read_b128 v[182:185], v237 offset:5120
	ds_read_b128 v[186:189], v237 offset:6144
	ds_read_b128 v[190:193], v237 offset:7168
	global_load_lds_dwordx4 v[194:195], off
	v_lshl_add_u64 v[194:195], s[72:73], 0, v[212:213]
	s_add_i32 m0, s51, 0xe000
	s_nop 0
	global_load_lds_dwordx4 v[194:195], off
	s_waitcnt vmcnt(8)
	s_barrier
	s_waitcnt lgkmcnt(0)
	v_mfma_f32_16x16x32_bf16 v[126:129], v[130:133], v[162:165], v[126:129]
	v_mfma_f32_16x16x32_bf16 v[126:129], v[134:137], v[166:169], v[126:129]
	s_add_i32 s54, s6, 2
	s_cmp_lt_u32 s54, s41
	v_mfma_f32_16x16x32_bf16 v[122:125], v[142:145], v[166:169], v[122:125]
	s_cselect_b64 s[14:15], -1, 0
	s_and_b64 s[58:59], s[14:15], exec
	v_mfma_f32_16x16x32_bf16 v[122:125], v[138:141], v[162:165], v[122:125]
	s_cselect_b32 s7, 0, s41
	s_sub_i32 s7, s6, s7
	v_mfma_f32_16x16x32_bf16 v[118:121], v[146:149], v[162:165], v[118:121]
	s_add_i32 s76, s7, 2
	s_and_b64 s[14:15], s[14:15], exec
	v_mfma_f32_16x16x32_bf16 v[118:121], v[150:153], v[166:169], v[118:121]
	s_cselect_b32 s7, s9, s17
	s_cselect_b32 s58, s8, s16
	v_mfma_f32_16x16x32_bf16 v[114:117], v[158:161], v[166:169], v[114:117]
	s_lshl_b64 s[14:15], s[76:77], s80
	s_add_u32 s72, s58, s14
	v_mfma_f32_16x16x32_bf16 v[114:117], v[154:157], v[162:165], v[114:117]
	s_addc_u32 s7, s7, s15
	s_add_i32 s14, s6, 3
	v_mfma_f32_16x16x32_bf16 v[98:101], v[154:157], v[170:173], v[98:101]
	s_cmp_lt_u32 s14, s41
	s_cselect_b64 s[14:15], -1, 0
	v_mfma_f32_16x16x32_bf16 v[98:101], v[158:161], v[174:177], v[98:101]
	s_and_b64 s[58:59], s[14:15], exec
	s_cselect_b32 s58, 0, s41
	v_mfma_f32_16x16x32_bf16 v[102:105], v[150:153], v[174:177], v[102:105]
	s_sub_i32 s58, s6, s58
	s_add_i32 s76, s58, 3
	v_mfma_f32_16x16x32_bf16 v[102:105], v[146:149], v[170:173], v[102:105]
	s_and_b64 s[14:15], s[14:15], exec
	s_cselect_b32 s58, s9, s17
	v_mfma_f32_16x16x32_bf16 v[106:109], v[138:141], v[170:173], v[106:109]
	s_cselect_b32 s59, s8, s16
	s_lshl_b64 s[14:15], s[76:77], s80
	v_mfma_f32_16x16x32_bf16 v[106:109], v[142:145], v[174:177], v[106:109]
	s_add_u32 s59, s59, s14
	s_addc_u32 s58, s58, s15
	v_mfma_f32_16x16x32_bf16 v[110:113], v[134:137], v[174:177], v[110:113]
	s_cmp_eq_u32 s39, s6
	s_cselect_b32 s15, s13, s7
	v_mfma_f32_16x16x32_bf16 v[110:113], v[130:133], v[170:173], v[110:113]
	s_cselect_b32 s14, s12, s72
	s_cselect_b32 s7, s21, s58
	v_mfma_f32_16x16x32_bf16 v[92:95], v[130:133], v[178:181], v[92:95]
	s_cselect_b32 s6, s20, s59
	s_cselect_b32 s59, s97, s53
	v_mfma_f32_16x16x32_bf16 v[92:95], v[134:137], v[182:185], v[92:95]
	s_cselect_b32 s58, s96, s52
	s_mov_b32 s76, 0x10000
	v_mfma_f32_16x16x32_bf16 v[88:91], v[142:145], v[182:185], v[88:91]
	v_mfma_f32_16x16x32_bf16 v[88:91], v[138:141], v[178:181], v[88:91]
	v_mfma_f32_16x16x32_bf16 v[84:87], v[146:149], v[178:181], v[84:87]
	v_mfma_f32_16x16x32_bf16 v[84:87], v[150:153], v[182:185], v[84:87]
	v_mfma_f32_16x16x32_bf16 v[80:83], v[158:161], v[182:185], v[80:83]
	v_mfma_f32_16x16x32_bf16 v[80:83], v[154:157], v[178:181], v[80:83]
	v_mfma_f32_16x16x32_bf16 v[64:67], v[154:157], v[186:189], v[64:67]
	v_mfma_f32_16x16x32_bf16 v[64:67], v[158:161], v[190:193], v[64:67]
	v_mfma_f32_16x16x32_bf16 v[68:71], v[150:153], v[190:193], v[68:71]
	v_mfma_f32_16x16x32_bf16 v[68:71], v[146:149], v[186:189], v[68:71]
	v_mfma_f32_16x16x32_bf16 v[72:75], v[138:141], v[186:189], v[72:75]
	v_mfma_f32_16x16x32_bf16 v[72:75], v[142:145], v[190:193], v[72:75]
	v_mfma_f32_16x16x32_bf16 v[76:79], v[134:137], v[190:193], v[76:79]
	v_mfma_f32_16x16x32_bf16 v[76:79], v[130:133], v[186:189], v[76:79]
	s_barrier
; #define PG8_STAGE(bufoff, gbase, voff) do { _Pragma("unroll") for (int _i = 0; _i < 2; ++_i) \
;     __builtin_amdgcn_global_load_lds((const unsigned*)((const char*)(gbase) + (voff)[_i]), (LAS unsigned*)(lds + (bufoff) + ldsw + _i * 8192), 16, 0, 0); } while (0)
; #define PG8_LDA(dst, b, h) do { _Pragma("unroll") for (int m = 0; m < 4; ++m) _Pragma("unroll") for (int k = 0; k < 2; ++k) dst[m][k] = *(const LAS bf16x8*)(lds + PG8_SA(b, h) + aoff + m * 2048 + k * 1024); } while (0)
; #define PG8_MMA(ai, bj, At, Bt) do { __builtin_amdgcn_s_setprio(1); _Pragma("unroll") for (int m = 0; m < 4; ++m) _Pragma("unroll") for (int n = 0; n < 2; ++n) _Pragma("unroll") for (int k = 0; k < 2; ++k) \
;     acc[ai][bj][m][n] = __builtin_amdgcn_mfma_f32_16x16x32_bf16(Bt[n][k], At[m][k], acc[ai][bj][m][n], 0, 0, 0); __builtin_amdgcn_s_setprio(0); } while (0)
; #define PG8_WAIT_V(n) asm volatile("s_waitcnt vmcnt(" #n ")" ::: "memory")
; #define PG8_WAIT_L(n) asm volatile("s_waitcnt lgkmcnt(" #n ")" ::: "memory")
; #define PG8_BAR __builtin_amdgcn_s_barrier()
; #define PG8_SCHED __builtin_amdgcn_sched_barrier(0)
; __device__ __forceinline__ void gemm_phase(const Ctx& cx, LAS unsigned char* lds, const GemmDesc& g) {
;     ...
;       PG8_LDA(At, 0, 1); PG8_STAGE(PG8_SB(0, 0), b2, voffB); PG8_STAGE(PG8_SB(0, 1), b2 + hstepB, voffB); PG8_STAGE(PG8_SA(0, 0), a2, voffA);
;       PG8_WAIT_V(8); PG8_WAIT_L(0); PG8_BAR; PG8_MMA(1, 0, At, B0); PG8_MMA(1, 1, At, B1); PG8_BAR; PG8_SCHED;
	s_add_i32 s55, s76, s36
	v_lshl_add_u64 v[194:195], s[58:59], 0, v[216:217]
	s_mov_b32 m0, s55
	ds_read_b128 v[162:165], v237 offset:16384
	ds_read_b128 v[166:169], v237 offset:17408
	ds_read_b128 v[170:173], v237 offset:18432
	ds_read_b128 v[174:177], v237 offset:19456
	ds_read_b128 v[178:181], v237 offset:20480
	ds_read_b128 v[182:185], v237 offset:21504
	ds_read_b128 v[186:189], v237 offset:22528
	ds_read_b128 v[190:193], v237 offset:23552
	global_load_lds_dwordx4 v[194:195], off
	s_add_i32 m0, s55, 0x2000
	v_lshl_add_u64 v[196:197], s[58:59], 0, v[214:215]
	s_add_u32 s58, s58, s30
	s_addc_u32 s59, s59, s31
	s_add_i32 s55, vcc_lo, s36
	global_load_lds_dwordx4 v[196:197], off
	v_lshl_add_u64 v[198:199], s[58:59], 0, v[216:217]
	s_mov_b32 m0, s55
	v_lshl_add_u64 v[200:201], s[58:59], 0, v[214:215]
	global_load_lds_dwordx4 v[198:199], off
	s_add_i32 m0, s55, 0x2000
	v_lshl_add_u64 v[202:203], s[14:15], 0, v[210:211]
	global_load_lds_dwordx4 v[200:201], off
	s_mov_b32 m0, s51
	s_nop 0
	global_load_lds_dwordx4 v[202:203], off
	v_lshl_add_u64 v[202:203], s[14:15], 0, v[212:213]
	s_mov_b32 m0, s43
	s_nop 0
	global_load_lds_dwordx4 v[202:203], off
	s_waitcnt vmcnt(8)
	s_barrier
	s_waitcnt lgkmcnt(0)
	v_mfma_f32_16x16x32_bf16 v[60:63], v[130:133], v[162:165], v[60:63]
	v_mfma_f32_16x16x32_bf16 v[60:63], v[134:137], v[166:169], v[60:63]
	v_mfma_f32_16x16x32_bf16 v[56:59], v[142:145], v[166:169], v[56:59]
	v_mfma_f32_16x16x32_bf16 v[56:59], v[138:141], v[162:165], v[56:59]
	v_mfma_f32_16x16x32_bf16 v[52:55], v[146:149], v[162:165], v[52:55]
	v_mfma_f32_16x16x32_bf16 v[52:55], v[150:153], v[166:169], v[52:55]
	v_mfma_f32_16x16x32_bf16 v[48:51], v[158:161], v[166:169], v[48:51]
	v_mfma_f32_16x16x32_bf16 v[48:51], v[154:157], v[162:165], v[48:51]
	v_mfma_f32_16x16x32_bf16 v[32:35], v[154:157], v[170:173], v[32:35]
	v_mfma_f32_16x16x32_bf16 v[32:35], v[158:161], v[174:177], v[32:35]
	v_mfma_f32_16x16x32_bf16 v[36:39], v[150:153], v[174:177], v[36:39]
	v_mfma_f32_16x16x32_bf16 v[36:39], v[146:149], v[170:173], v[36:39]
	v_mfma_f32_16x16x32_bf16 v[40:43], v[138:141], v[170:173], v[40:43]
	v_mfma_f32_16x16x32_bf16 v[40:43], v[142:145], v[174:177], v[40:43]
	v_mfma_f32_16x16x32_bf16 v[44:47], v[134:137], v[174:177], v[44:47]
	v_mfma_f32_16x16x32_bf16 v[44:47], v[130:133], v[170:173], v[44:47]
	v_mfma_f32_16x16x32_bf16 v[28:31], v[130:133], v[178:181], v[28:31]
	v_mfma_f32_16x16x32_bf16 v[28:31], v[134:137], v[182:185], v[28:31]
	v_mfma_f32_16x16x32_bf16 v[24:27], v[142:145], v[182:185], v[24:27]
	v_mfma_f32_16x16x32_bf16 v[24:27], v[138:141], v[178:181], v[24:27]
	v_mfma_f32_16x16x32_bf16 v[20:23], v[146:149], v[178:181], v[20:23]
	v_mfma_f32_16x16x32_bf16 v[20:23], v[150:153], v[182:185], v[20:23]
	v_mfma_f32_16x16x32_bf16 v[16:19], v[158:161], v[182:185], v[16:19]
	v_mfma_f32_16x16x32_bf16 v[16:19], v[154:157], v[178:181], v[16:19]
	v_mfma_f32_16x16x32_bf16 v[0:3], v[154:157], v[186:189], v[0:3]
	v_mfma_f32_16x16x32_bf16 v[0:3], v[158:161], v[190:193], v[0:3]
	v_mfma_f32_16x16x32_bf16 v[4:7], v[150:153], v[190:193], v[4:7]
	v_mfma_f32_16x16x32_bf16 v[4:7], v[146:149], v[186:189], v[4:7]
	v_mfma_f32_16x16x32_bf16 v[8:11], v[138:141], v[186:189], v[8:11]
	v_mfma_f32_16x16x32_bf16 v[8:11], v[142:145], v[190:193], v[8:11]
	v_mfma_f32_16x16x32_bf16 v[12:15], v[134:137], v[190:193], v[12:15]
	v_mfma_f32_16x16x32_bf16 v[12:15], v[130:133], v[186:189], v[12:15]
	s_barrier
; #define PG8_STAGE(bufoff, gbase, voff) do { _Pragma("unroll") for (int _i = 0; _i < 2; ++_i) \
;     __builtin_amdgcn_global_load_lds((const unsigned*)((const char*)(gbase) + (voff)[_i]), (LAS unsigned*)(lds + (bufoff) + ldsw + _i * 8192), 16, 0, 0); } while (0)
; #define PG8_LDA(dst, b, h) do { _Pragma("unroll") for (int m = 0; m < 4; ++m) _Pragma("unroll") for (int k = 0; k < 2; ++k) dst[m][k] = *(const LAS bf16x8*)(lds + PG8_SA(b, h) + aoff + m * 2048 + k * 1024); } while (0)
; #define PG8_LDB(dst, b, h) do { _Pragma("unroll") for (int n = 0; n < 2; ++n) _Pragma("unroll") for (int k = 0; k < 2; ++k) dst[n][k] = *(const LAS bf16x8*)(lds + PG8_SB(b, h) + boff + n * 2048 + k * 1024); } while (0)
; #define PG8_MMA(ai, bj, At, Bt) do { __builtin_amdgcn_s_setprio(1); _Pragma("unroll") for (int m = 0; m < 4; ++m) _Pragma("unroll") for (int n = 0; n < 2; ++n) _Pragma("unroll") for (int k = 0; k < 2; ++k) \
;     acc[ai][bj][m][n] = __builtin_amdgcn_mfma_f32_16x16x32_bf16(Bt[n][k], At[m][k], acc[ai][bj][m][n], 0, 0, 0); __builtin_amdgcn_s_setprio(0); } while (0)
; #define PG8_WAIT_V(n) asm volatile("s_waitcnt vmcnt(" #n ")" ::: "memory")
; #define PG8_WAIT_L(n) asm volatile("s_waitcnt lgkmcnt(" #n ")" ::: "memory")
; #define PG8_BAR __builtin_amdgcn_s_barrier()
; #define PG8_SCHED __builtin_amdgcn_sched_barrier(0)
; __device__ __forceinline__ void gemm_phase(const Ctx& cx, LAS unsigned char* lds, const GemmDesc& g) {
;     ...
;       PG8_LDB(B0, 1, 0); PG8_LDB(B1, 1, 1); PG8_SCHED; PG8_LDA(At, 1, 0); PG8_STAGE(PG8_SA(0, 1), a2 + hstepA, voffA);
;       PG8_WAIT_V(8); PG8_WAIT_L(0); PG8_BAR; PG8_MMA(0, 0, At, B0); PG8_MMA(0, 1, At, B1); PG8_BAR; PG8_SCHED;
;       PG8_LDA(At, 1, 1); PG8_STAGE(PG8_SB(1, 0), b3, voffB); PG8_STAGE(PG8_SB(1, 1), b3 + hstepB, voffB); PG8_STAGE(PG8_SA(1, 0), a3, voffA);
;       PG8_WAIT_V(8); PG8_WAIT_L(0); PG8_BAR; PG8_MMA(1, 0, At, B0); PG8_MMA(1, 1, At, B1); PG8_BAR; PG8_SCHED;
;     }
;     if (wr == 0) PG8_BAR;
.Lk_p2:
	s_add_i32 s55, 0, 0x18000
	v_add_u32_e32 v96, s55, v252
	s_add_i32 s58, 0, 0x1c000
	ds_read_b128 v[130:133], v96
	ds_read_b128 v[134:137], v96 offset:1024
	ds_read_b128 v[138:141], v96 offset:2048
	ds_read_b128 v[142:145], v96 offset:3072
	v_add_u32_e32 v96, s58, v252
	ds_read_b128 v[146:149], v96
	ds_read_b128 v[150:153], v96 offset:1024
	ds_read_b128 v[154:157], v96 offset:2048
	ds_read_b128 v[158:161], v96 offset:3072
	s_add_u32 s14, s14, s28
	s_addc_u32 s15, s15, s29
	s_mov_b32 m0, s40
	v_lshl_add_u64 v[202:203], s[14:15], 0, v[210:211]
	ds_read_b128 v[162:165], v237 offset:32768
	ds_read_b128 v[166:169], v237 offset:33792
	ds_read_b128 v[170:173], v237 offset:34816
	ds_read_b128 v[174:177], v237 offset:35840
	ds_read_b128 v[178:181], v237 offset:36864
	ds_read_b128 v[182:185], v237 offset:37888
	ds_read_b128 v[186:189], v237 offset:38912
	ds_read_b128 v[190:193], v237 offset:39936
	global_load_lds_dwordx4 v[202:203], off
	v_lshl_add_u64 v[202:203], s[14:15], 0, v[212:213]
	s_mov_b32 m0, s37
	s_nop 0
	global_load_lds_dwordx4 v[202:203], off
	s_waitcnt vmcnt(8)
	s_barrier
	s_waitcnt lgkmcnt(0)
	v_mfma_f32_16x16x32_bf16 v[126:129], v[130:133], v[162:165], v[126:129]
	v_mfma_f32_16x16x32_bf16 v[126:129], v[134:137], v[166:169], v[126:129]
	v_mfma_f32_16x16x32_bf16 v[122:125], v[142:145], v[166:169], v[122:125]
	v_mfma_f32_16x16x32_bf16 v[122:125], v[138:141], v[162:165], v[122:125]
	v_mfma_f32_16x16x32_bf16 v[118:121], v[146:149], v[162:165], v[118:121]
	v_mfma_f32_16x16x32_bf16 v[118:121], v[150:153], v[166:169], v[118:121]
	v_mfma_f32_16x16x32_bf16 v[114:117], v[158:161], v[166:169], v[114:117]
	v_mfma_f32_16x16x32_bf16 v[114:117], v[154:157], v[162:165], v[114:117]
	v_mfma_f32_16x16x32_bf16 v[98:101], v[154:157], v[170:173], v[98:101]
	v_mfma_f32_16x16x32_bf16 v[98:101], v[158:161], v[174:177], v[98:101]
	v_mfma_f32_16x16x32_bf16 v[102:105], v[150:153], v[174:177], v[102:105]
	v_mfma_f32_16x16x32_bf16 v[102:105], v[146:149], v[170:173], v[102:105]
	v_mfma_f32_16x16x32_bf16 v[106:109], v[138:141], v[170:173], v[106:109]
	v_mfma_f32_16x16x32_bf16 v[106:109], v[142:145], v[174:177], v[106:109]
	v_mfma_f32_16x16x32_bf16 v[110:113], v[134:137], v[174:177], v[110:113]
	v_mfma_f32_16x16x32_bf16 v[110:113], v[130:133], v[170:173], v[110:113]
	v_mfma_f32_16x16x32_bf16 v[92:95], v[130:133], v[178:181], v[92:95]
	v_mfma_f32_16x16x32_bf16 v[92:95], v[134:137], v[182:185], v[92:95]
	v_mfma_f32_16x16x32_bf16 v[88:91], v[142:145], v[182:185], v[88:91]
	v_mfma_f32_16x16x32_bf16 v[88:91], v[138:141], v[178:181], v[88:91]
	v_mfma_f32_16x16x32_bf16 v[84:87], v[146:149], v[178:181], v[84:87]
	v_mfma_f32_16x16x32_bf16 v[84:87], v[150:153], v[182:185], v[84:87]
	v_mfma_f32_16x16x32_bf16 v[80:83], v[158:161], v[182:185], v[80:83]
	v_mfma_f32_16x16x32_bf16 v[80:83], v[154:157], v[178:181], v[80:83]
	v_mfma_f32_16x16x32_bf16 v[64:67], v[154:157], v[186:189], v[64:67]
	v_mfma_f32_16x16x32_bf16 v[64:67], v[158:161], v[190:193], v[64:67]
	v_mfma_f32_16x16x32_bf16 v[68:71], v[150:153], v[190:193], v[68:71]
	v_mfma_f32_16x16x32_bf16 v[68:71], v[146:149], v[186:189], v[68:71]
	v_mfma_f32_16x16x32_bf16 v[72:75], v[138:141], v[186:189], v[72:75]
	v_mfma_f32_16x16x32_bf16 v[72:75], v[142:145], v[190:193], v[72:75]
	v_mfma_f32_16x16x32_bf16 v[76:79], v[134:137], v[190:193], v[76:79]
	v_mfma_f32_16x16x32_bf16 v[76:79], v[130:133], v[186:189], v[76:79]
	s_barrier
	s_add_i32 s14, s55, s36
	v_lshl_add_u64 v[194:195], v[194:195], 0, s[92:93]
	s_mov_b32 m0, s14
	ds_read_b128 v[162:165], v237 offset:49152
	ds_read_b128 v[166:169], v237 offset:50176
	ds_read_b128 v[170:173], v237 offset:51200
	ds_read_b128 v[174:177], v237 offset:52224
	ds_read_b128 v[178:181], v237 offset:53248
	ds_read_b128 v[182:185], v237 offset:54272
	ds_read_b128 v[186:189], v237 offset:55296
	ds_read_b128 v[190:193], v237 offset:56320
	global_load_lds_dwordx4 v[194:195], off
	v_lshl_add_u64 v[194:195], v[196:197], 0, s[92:93]
	s_add_i32 m0, s14, 0x2000
	s_add_i32 s14, s58, s36
	global_load_lds_dwordx4 v[194:195], off
	v_lshl_add_u64 v[194:195], v[198:199], 0, s[92:93]
	s_mov_b32 m0, s14
	s_nop 0
	global_load_lds_dwordx4 v[194:195], off
	v_lshl_add_u64 v[194:195], v[200:201], 0, s[92:93]
	s_add_i32 m0, s14, 0x2000
	s_nop 0
	global_load_lds_dwordx4 v[194:195], off
	v_lshl_add_u64 v[194:195], s[6:7], 0, v[210:211]
	s_mov_b32 m0, s0
	s_nop 0
	global_load_lds_dwordx4 v[194:195], off
	v_lshl_add_u64 v[194:195], s[6:7], 0, v[212:213]
	s_mov_b32 m0, s1
	s_nop 0
	global_load_lds_dwordx4 v[194:195], off
	s_waitcnt vmcnt(8)
	s_barrier
	s_waitcnt lgkmcnt(0)
	v_mfma_f32_16x16x32_bf16 v[60:63], v[130:133], v[162:165], v[60:63]
	v_mfma_f32_16x16x32_bf16 v[60:63], v[134:137], v[166:169], v[60:63]
	v_mfma_f32_16x16x32_bf16 v[56:59], v[142:145], v[166:169], v[56:59]
	v_mfma_f32_16x16x32_bf16 v[56:59], v[138:141], v[162:165], v[56:59]
	v_mfma_f32_16x16x32_bf16 v[52:55], v[146:149], v[162:165], v[52:55]
	v_mfma_f32_16x16x32_bf16 v[52:55], v[150:153], v[166:169], v[52:55]
	v_mfma_f32_16x16x32_bf16 v[48:51], v[158:161], v[166:169], v[48:51]
	v_mfma_f32_16x16x32_bf16 v[48:51], v[154:157], v[162:165], v[48:51]
	v_mfma_f32_16x16x32_bf16 v[32:35], v[154:157], v[170:173], v[32:35]
	v_mfma_f32_16x16x32_bf16 v[32:35], v[158:161], v[174:177], v[32:35]
	v_mfma_f32_16x16x32_bf16 v[36:39], v[150:153], v[174:177], v[36:39]
	v_mfma_f32_16x16x32_bf16 v[36:39], v[146:149], v[170:173], v[36:39]
	v_mfma_f32_16x16x32_bf16 v[40:43], v[138:141], v[170:173], v[40:43]
	v_mfma_f32_16x16x32_bf16 v[40:43], v[142:145], v[174:177], v[40:43]
	v_mfma_f32_16x16x32_bf16 v[44:47], v[134:137], v[174:177], v[44:47]
	v_mfma_f32_16x16x32_bf16 v[44:47], v[130:133], v[170:173], v[44:47]
	v_mfma_f32_16x16x32_bf16 v[28:31], v[130:133], v[178:181], v[28:31]
	v_mfma_f32_16x16x32_bf16 v[28:31], v[134:137], v[182:185], v[28:31]
	v_mfma_f32_16x16x32_bf16 v[24:27], v[142:145], v[182:185], v[24:27]
	v_mfma_f32_16x16x32_bf16 v[24:27], v[138:141], v[178:181], v[24:27]
	v_mfma_f32_16x16x32_bf16 v[20:23], v[146:149], v[178:181], v[20:23]
	v_mfma_f32_16x16x32_bf16 v[20:23], v[150:153], v[182:185], v[20:23]
	v_mfma_f32_16x16x32_bf16 v[16:19], v[158:161], v[182:185], v[16:19]
	v_mfma_f32_16x16x32_bf16 v[16:19], v[154:157], v[178:181], v[16:19]
	v_mfma_f32_16x16x32_bf16 v[0:3], v[154:157], v[186:189], v[0:3]
	v_mfma_f32_16x16x32_bf16 v[0:3], v[158:161], v[190:193], v[0:3]
	v_mfma_f32_16x16x32_bf16 v[4:7], v[150:153], v[190:193], v[4:7]
	v_mfma_f32_16x16x32_bf16 v[4:7], v[146:149], v[186:189], v[4:7]
	v_mfma_f32_16x16x32_bf16 v[8:11], v[138:141], v[186:189], v[8:11]
	v_mfma_f32_16x16x32_bf16 v[8:11], v[142:145], v[190:193], v[8:11]
	v_mfma_f32_16x16x32_bf16 v[12:15], v[134:137], v[190:193], v[12:15]
	v_mfma_f32_16x16x32_bf16 v[12:15], v[130:133], v[186:189], v[12:15]
	s_barrier
	s_add_u32 s52, s52, 0x100
	s_addc_u32 s53, s53, 0
	s_cmp_ge_u32 s54, s10
	s_mov_b32 s6, s54
	s_cbranch_scc0 .LBB0_358
	v_readlane_b32 s6, v255, 19
	v_readlane_b32 s7, v255, 20
	s_and_b64 vcc, exec, s[6:7]
	s_cbranch_vccz .LBB0_361
	s_barrier
